# modulation-vector hoist also in the second-FFN LayerNorm variant (three LayerNorm loops)
# baseline (speedup 1.0000x reference)
.LBB0_1437:
	s_lshl_b32 s8, s22, 8
	s_add_i32 s8, s8, s14
	s_waitcnt vmcnt(5)
	v_mov_b64_e32 v[76:77], v[80:81]
	s_cmp_lt_u32 s22, 8
	s_waitcnt vmcnt(4)
	v_mov_b64_e32 v[48:49], v[92:93]
	v_mov_b64_e32 v[56:57], v[88:89]
	v_mov_b64_e32 v[68:69], v[84:85]
	v_mov_b64_e32 v[78:79], v[82:83]
	s_cselect_b32 s16, s8, s24
	v_cndmask_b32_e64 v80, 0, 1, s[4:5]
	v_mov_b64_e32 v[50:51], v[94:95]
	v_mov_b64_e32 v[58:59], v[90:91]
	v_mov_b64_e32 v[70:71], v[86:87]
	s_ashr_i32 s17, s16, 31
	s_add_i32 s92, s16, 0xffffc000
	v_cmp_ne_u32_e64 s[8:9], 1, v80
	s_andn2_b64 vcc, exec, s[4:5]
	v_lshlrev_b32_e32 v132, 2, v120
	s_cbranch_vccnz .LBB0_1439
	s_lshr_b32 s11, s92, 2
	s_ashr_i32 s10, s16, 11
	s_add_i32 s11, s11, 8
	s_cmpk_lt_i32 s16, 0x4000
	s_cselect_b32 s10, s10, s11
	s_addk_i32 s10, 0x88
	s_mul_hi_i32 s11, s10, 0x9000
	s_mul_i32 s10, s10, 0x9000
	s_add_u32 s10, s3, s10
	s_addc_u32 s11, s20, s11
	s_add_u32 s18, s10, 0x1000
	s_addc_u32 s19, s11, 0
	s_cmp_eq_u32 s22, 0
	s_cbranch_scc1 .Lmy_lnh_c_reload
	s_cmp_lg_u32 s22, 8
	s_cbranch_scc1 .Lmy_lnh_c_copy
.Lmy_lnh_c_reload:
	global_load_dwordx4 v[178:181], v132, s[10:11] offset:1024
	global_load_dwordx4 v[182:185], v132, s[10:11] offset:2048
	global_load_dwordx4 v[186:189], v129, s[18:19]
	global_load_dwordx4 v[190:193], v130, s[18:19]
	global_load_dwordx4 v[212:215], v132, s[18:19]
	global_load_dwordx4 v[216:219], v132, s[10:11] offset:3072
	global_load_dwordx4 v[222:225], v132, s[10:11]
	global_load_dwordx4 v[226:229], v131, s[18:19]
	s_waitcnt vmcnt(0)
.Lmy_lnh_c_copy:
	v_mov_b64_e32 v[40:41], v[178:179]
	v_mov_b64_e32 v[42:43], v[180:181]
	v_mov_b64_e32 v[52:53], v[182:183]
	v_mov_b64_e32 v[54:55], v[184:185]
	v_mov_b64_e32 v[32:33], v[186:187]
	v_mov_b64_e32 v[34:35], v[188:189]
	v_mov_b64_e32 v[44:45], v[190:191]
	v_mov_b64_e32 v[46:47], v[192:193]
	v_mov_b64_e32 v[36:37], v[212:213]
	v_mov_b64_e32 v[38:39], v[214:215]
	v_mov_b64_e32 v[72:73], v[216:217]
	v_mov_b64_e32 v[74:75], v[218:219]
	v_mov_b64_e32 v[64:65], v[222:223]
	v_mov_b64_e32 v[66:67], v[224:225]
	v_mov_b64_e32 v[60:61], v[226:227]
	v_mov_b64_e32 v[62:63], v[228:229]
